# 64-byte alignment of the hot loop heads (GEMM K loops, FoX / NSA sel / win tile loops)
# baseline (speedup 1.0000x reference)
;     __device__ __forceinline__ bool next(int i, Unit& u) const { Unit t; if (!base.next(i / 3, t)) return false; const int br = i % 3; u.pm = t.pm + 128 * br; u.pn = t.pn + 4 * br; return true; }
; template <class Epi, class Sched, bool ALIGN_EPI = false, bool SP2 = false>
; __device__ __forceinline__ void gemm_phase(PG8_LAS unsigned char* lds, const Gemm g, const Sched& S, const Epi& E) {
;     ...
;     for (;;) {
;         const bool has_next = S.next(ui + 1, nxt);
;         const char* nA = has_next ? (const char*)g.A + (size_t)nxt.pm * tstep : cA; const char* nB = has_next ? (const char*)g.Bt + (size_t)nxt.pn * tstep : cB;
;         for (int t = 0; t < nt; t += 2) {
;             const bool last = (t == nt - 2);
;             const char* a1 = cA + (size_t)(t + 1) * kstep;
;             const char* a2 = last ? nA : cA + (size_t)(t + 2) * kstep; const char* b2 = last ? nB : cB + (size_t)(t + 2) * kstep;
;             const char* a3 = a2 + kstep; const char* b3 = b2 + kstep;
.LBB0_36:
	s_ashr_i32 s31, s30, 31
	s_lshl_b64 s[44:45], s[30:31], 18
	v_readlane_b32 s13, v253, 29
	s_add_u32 s44, s13, s44
	v_readlane_b32 s13, v253, 30
	s_addc_u32 s45, s13, s45
	s_and_b64 s[46:47], s[38:39], exec
	s_cselect_b32 s13, s45, s7
	s_cselect_b32 s18, s44, s6
	s_ashr_i32 s43, s42, 31
	s_lshl_b64 s[46:47], s[42:43], 18
	v_readlane_b32 s52, v252, 57
	v_readlane_b32 s53, v252, 58
	s_add_u32 s46, s52, s46
	s_addc_u32 s47, s53, s47
	s_and_b64 s[52:53], s[38:39], exec
	s_cselect_b32 s31, s47, s51
	s_cselect_b32 s41, s46, s50
	s_add_u32 s6, s6, 0x20080
	s_addc_u32 s7, s7, 0
	s_add_u32 s43, s50, 0x100
	v_mov_b32_e32 v192, 0x3ecc95a3
	s_addc_u32 s49, s51, 0
	s_mov_b32 s69, -2
	.p2align	6

;     __device__ __forceinline__ bool next(int i, Unit& u) const { Unit t; if (!base.next(i / 3, t)) return false; const int br = i % 3; u.pm = t.pm + 128 * br; u.pn = t.pn + 4 * br; return true; }
; template <class Epi, class Sched, bool ALIGN_EPI = false, bool SP2 = false>
; __device__ __forceinline__ void gemm_phase(PG8_LAS unsigned char* lds, const Gemm g, const Sched& S, const Epi& E) {
;     ...
;     f32x4 acc[2][2][4][2];
; #pragma unroll
;     for (int a = 0; a < 2; ++a)
; #pragma unroll
;         for (int b = 0; b < 2; ++b)
; #pragma unroll
;             for (int m = 0; m < 4; ++m)
; #pragma unroll
;                 for (int n = 0; n < 2; ++n) acc[a][b][m][n] = (f32x4){0.f, 0.f, 0.f, 0.f};
;     ...
;         const bool has_next = S.next(ui + 1, nxt);
;         const char* nA = has_next ? (const char*)g.A + (size_t)nxt.pm * tstep : cA; const char* nB = has_next ? (const char*)g.Bt + (size_t)nxt.pn * tstep : cB;
;         for (int t = 0; t < nt; t += 2) {
;             const bool last = (t == nt - 2);
;             const char* a1 = cA + (size_t)(t + 1) * kstep;
;             const char* a2 = last ? nA : cA + (size_t)(t + 2) * kstep; const char* b2 = last ? nB : cB + (size_t)(t + 2) * kstep;
;             const char* a3 = a2 + kstep; const char* b3 = b2 + kstep;
.LBB0_128:
	s_ashr_i32 s41, s40, 31
	s_lshl_b64 s[42:43], s[40:41], 19
	s_add_u32 s42, s72, s42
	s_addc_u32 s43, s73, s43
	s_and_b64 s[44:45], s[38:39], exec
	s_cselect_b32 s18, s43, s49
	s_cselect_b32 s41, s42, s48
	s_ashr_i32 s31, s30, 31
	s_lshl_b64 s[44:45], s[30:31], 19
	v_readlane_b32 s50, v252, 59
	v_readlane_b32 s51, v252, 60
	s_add_u32 s44, s50, s44
	s_addc_u32 s45, s51, s45
	s_and_b64 s[50:51], s[38:39], exec
	s_cselect_b32 s31, s45, s7
	s_cselect_b32 s64, s44, s6
	s_add_u32 s48, s48, 0x40080
	s_addc_u32 s49, s49, 0
	s_add_u32 s65, s6, 0x100
	v_mov_b32_e32 v2, 0
	s_addc_u32 s66, s7, 0
	s_mov_b32 s67, -2
	v_mov_b32_e32 v3, v2
	v_mov_b32_e32 v4, v2
	v_mov_b32_e32 v5, v2
	v_mov_b32_e32 v6, v2
	v_mov_b32_e32 v7, v2
	v_mov_b32_e32 v8, v2
	v_mov_b32_e32 v9, v2
	v_mov_b32_e32 v10, v2
	v_mov_b32_e32 v11, v2
	v_mov_b32_e32 v12, v2
	v_mov_b32_e32 v13, v2
	v_mov_b32_e32 v14, v2
	v_mov_b32_e32 v15, v2
	v_mov_b32_e32 v16, v2
	v_mov_b32_e32 v17, v2
	v_mov_b32_e32 v18, v2
	v_mov_b32_e32 v19, v2
	v_mov_b32_e32 v20, v2
	v_mov_b32_e32 v21, v2
	v_mov_b32_e32 v22, v2
	v_mov_b32_e32 v23, v2
	v_mov_b32_e32 v24, v2
	v_mov_b32_e32 v25, v2
	v_mov_b32_e32 v26, v2
	v_mov_b32_e32 v27, v2
	v_mov_b32_e32 v28, v2
	v_mov_b32_e32 v29, v2
	v_mov_b32_e32 v30, v2
	v_mov_b32_e32 v31, v2
	v_mov_b32_e32 v32, v2
	v_mov_b32_e32 v33, v2
	v_mov_b32_e32 v66, v2
	v_mov_b32_e32 v67, v2
	v_mov_b32_e32 v68, v2
	v_mov_b32_e32 v69, v2
	v_mov_b32_e32 v70, v2
	v_mov_b32_e32 v71, v2
	v_mov_b32_e32 v72, v2
	v_mov_b32_e32 v73, v2
	v_mov_b32_e32 v74, v2
	v_mov_b32_e32 v75, v2
	v_mov_b32_e32 v76, v2
	v_mov_b32_e32 v77, v2
	v_mov_b32_e32 v78, v2
	v_mov_b32_e32 v79, v2
	v_mov_b32_e32 v80, v2
	v_mov_b32_e32 v81, v2
	v_mov_b32_e32 v82, v2
	v_mov_b32_e32 v83, v2
	v_mov_b32_e32 v84, v2
	v_mov_b32_e32 v85, v2
	v_mov_b32_e32 v86, v2
	v_mov_b32_e32 v87, v2
	v_mov_b32_e32 v88, v2
	v_mov_b32_e32 v89, v2
	v_mov_b32_e32 v90, v2
	v_mov_b32_e32 v91, v2
	v_mov_b32_e32 v92, v2
	v_mov_b32_e32 v93, v2
	v_mov_b32_e32 v94, v2
	v_mov_b32_e32 v95, v2
	v_mov_b32_e32 v96, v2
	v_mov_b32_e32 v97, v2
	v_mov_b32_e32 v34, v2
	v_mov_b32_e32 v35, v2
	v_mov_b32_e32 v36, v2
	v_mov_b32_e32 v37, v2
	v_mov_b32_e32 v38, v2
	v_mov_b32_e32 v39, v2
	v_mov_b32_e32 v40, v2
	v_mov_b32_e32 v41, v2
	v_mov_b32_e32 v42, v2
	v_mov_b32_e32 v43, v2
	v_mov_b32_e32 v44, v2
	v_mov_b32_e32 v45, v2
	v_mov_b32_e32 v46, v2
	v_mov_b32_e32 v47, v2
	v_mov_b32_e32 v48, v2
	v_mov_b32_e32 v49, v2
	v_mov_b32_e32 v50, v2
	v_mov_b32_e32 v51, v2
	v_mov_b32_e32 v52, v2
	v_mov_b32_e32 v53, v2
	v_mov_b32_e32 v54, v2
	v_mov_b32_e32 v55, v2
	v_mov_b32_e32 v56, v2
	v_mov_b32_e32 v57, v2
	v_mov_b32_e32 v58, v2
	v_mov_b32_e32 v59, v2
	v_mov_b32_e32 v60, v2
	v_mov_b32_e32 v61, v2
	v_mov_b32_e32 v62, v2
	v_mov_b32_e32 v63, v2
	v_mov_b32_e32 v64, v2
	v_mov_b32_e32 v65, v2
	v_mov_b32_e32 v98, v2
	v_mov_b32_e32 v99, v2
	v_mov_b32_e32 v100, v2
	v_mov_b32_e32 v101, v2
	v_mov_b32_e32 v102, v2
	v_mov_b32_e32 v103, v2
	v_mov_b32_e32 v104, v2
	v_mov_b32_e32 v105, v2
	v_mov_b32_e32 v114, v2
	v_mov_b32_e32 v115, v2
	v_mov_b32_e32 v116, v2
	v_mov_b32_e32 v117, v2
	v_mov_b32_e32 v118, v2
	v_mov_b32_e32 v119, v2
	v_mov_b32_e32 v120, v2
	v_mov_b32_e32 v121, v2
	v_mov_b32_e32 v122, v2
	v_mov_b32_e32 v123, v2
	v_mov_b32_e32 v124, v2
	v_mov_b32_e32 v125, v2
	v_mov_b32_e32 v126, v2
	v_mov_b32_e32 v127, v2
	v_mov_b32_e32 v128, v2
	v_mov_b32_e32 v129, v2
	v_mov_b32_e32 v130, v2
	v_mov_b32_e32 v131, v2
	v_mov_b32_e32 v132, v2
	v_mov_b32_e32 v133, v2
	v_mov_b32_e32 v134, v2
	v_mov_b32_e32 v135, v2
	v_mov_b32_e32 v136, v2
	v_mov_b32_e32 v137, v2
	.p2align	6

.LBB0_171:
	s_and_b64 s[0:1], exec, s[56:57]
	s_cselect_b32 s7, -1, s13
	s_add_u32 s0, s52, -1
	s_addc_u32 s1, s53, -1
	s_and_b64 s[52:53], s[0:1], s[52:53]
	s_waitcnt lgkmcnt(0)
	s_barrier
	s_and_b64 vcc, exec, s[48:49]
	s_mov_b32 s13, s6
	s_cbranch_vccnz .LBB0_159
	.p2align	6

.LBB0_307:
	s_and_b64 s[0:1], exec, s[46:47]
	s_cselect_b32 s18, -1, s7
	s_add_u32 s0, s44, -1
	s_addc_u32 s1, s45, -1
	s_and_b64 s[44:45], s[0:1], s[44:45]
	s_waitcnt lgkmcnt(0)
	s_barrier
	s_and_b64 vcc, exec, s[40:41]
	s_mov_b32 s0, s6
	s_cbranch_vccnz .LBB0_335
	.p2align	6

; __device__ __forceinline__ float ex2(float x) { return __builtin_amdgcn_exp2f(x); }
; template <int MODE> ...
;     ...
;             float ps = 0.f;
; #pragma unroll
;             for (int r = 0; r < 16; ++r) { s0[r] = ex2(s0[r]); s1[r] = ex2(s1[r]); ps += s0[r] + s1[r]; }
;             l += ps;
.LBB0_341:
	v_add_f32_e32 v0, v96, v0
	v_add_f32_e32 v0, 0, v0
	v_add_f32_e32 v10, v81, v14
	v_add_f32_e32 v0, v10, v0
	v_add_f32_e32 v10, v82, v15
	v_add_f32_e32 v0, v10, v0
	v_add_f32_e32 v10, v83, v68
	v_add_f32_e32 v0, v10, v0
	v_add_f32_e32 v10, v84, v69
	v_add_f32_e32 v0, v10, v0
	v_add_f32_e32 v10, v85, v70
	v_add_f32_e32 v0, v10, v0
	v_add_f32_e32 v10, v86, v71
	v_add_f32_e32 v0, v10, v0
	v_add_f32_e32 v10, v87, v72
	v_add_f32_e32 v0, v10, v0
	v_add_f32_e32 v10, v88, v73
	v_add_f32_e32 v0, v10, v0
	v_add_f32_e32 v10, v89, v74
	v_add_f32_e32 v0, v10, v0
	v_add_f32_e32 v10, v90, v75
	v_add_f32_e32 v0, v10, v0
	v_add_f32_e32 v10, v91, v76
	v_add_f32_e32 v0, v10, v0
	v_add_f32_e32 v10, v92, v77
	v_add_f32_e32 v0, v10, v0
	v_add_f32_e32 v10, v93, v78
	v_add_f32_e32 v0, v10, v0
	v_add_f32_e32 v10, v94, v79
	s_and_b64 s[0:1], exec, s[46:47]
	v_add_f32_e32 v0, v10, v0
	v_add_f32_e32 v10, v95, v80
	s_cselect_b32 s18, -1, s48
	s_add_u32 s0, s44, -1
	v_add_f32_e32 v0, v10, v0
	s_addc_u32 s1, s45, -1
	v_add_f32_e32 v188, v188, v0
	s_and_b64 s[44:45], s[0:1], s[44:45]
	s_mov_b64 s[0:1], s[40:41]
	s_waitcnt lgkmcnt(0)
	s_barrier
	s_and_b64 vcc, exec, s[0:1]
	s_mov_b32 s0, s29
	s_cbranch_vccnz .LBB0_211
	.p2align	6

;     __device__ __forceinline__ bool next(int i, Unit& u) const { Unit t; if (!base.next(i / 3, t)) return false; const int br = i % 3; u.pm = t.pm + 128 * br; u.pn = t.pn + 4 * br; return true; }
; template <class Epi, class Sched, bool ALIGN_EPI = false, bool SP2 = false>
; __device__ __forceinline__ void gemm_phase(PG8_LAS unsigned char* lds, const Gemm g, const Sched& S, const Epi& E) {
;     ...
;     f32x4 acc[2][2][4][2];
; #pragma unroll
;     for (int a = 0; a < 2; ++a)
; #pragma unroll
;         for (int b = 0; b < 2; ++b)
; #pragma unroll
;             for (int m = 0; m < 4; ++m)
; #pragma unroll
;                 for (int n = 0; n < 2; ++n) acc[a][b][m][n] = (f32x4){0.f, 0.f, 0.f, 0.f};
;     ...
;         const bool has_next = S.next(ui + 1, nxt);
;         const char* nA = has_next ? (const char*)g.A + (size_t)nxt.pm * tstep : cA; const char* nB = has_next ? (const char*)g.Bt + (size_t)nxt.pn * tstep : cB;
;         for (int t = 0; t < nt; t += 2) {
;             const bool last = (t == nt - 2);
;             const char* a1 = cA + (size_t)(t + 1) * kstep;
;             const char* a2 = last ? nA : cA + (size_t)(t + 2) * kstep; const char* b2 = last ? nB : cB + (size_t)(t + 2) * kstep;
;             const char* a3 = a2 + kstep; const char* b3 = b2 + kstep;
.LBB0_703:
	s_ashr_i32 s31, s30, 31
	s_lshl_b64 s[44:45], s[30:31], 19
	s_add_u32 s44, s72, s44
	s_addc_u32 s45, s73, s45
	s_and_b64 s[46:47], s[38:39], exec
	s_cselect_b32 s31, s45, s49
	s_cselect_b32 s41, s44, s48
	s_ashr_i32 s27, s26, 31
	s_lshl_b64 s[46:47], s[26:27], 19
	v_readlane_b32 s50, v252, 61
	v_readlane_b32 s51, v252, 62
	s_add_u32 s46, s50, s46
	s_addc_u32 s47, s51, s47
	s_and_b64 s[50:51], s[38:39], exec
	s_cselect_b32 s27, s47, s7
	s_cselect_b32 s62, s46, s6
	s_add_u32 s48, s48, 0x40080
	s_addc_u32 s49, s49, 0
	s_add_u32 s63, s6, 0x100
	v_mov_b32_e32 v2, 0
	s_addc_u32 s64, s7, 0
	s_mov_b32 s65, -2
	v_mov_b32_e32 v3, v2
	v_mov_b32_e32 v4, v2
	v_mov_b32_e32 v5, v2
	v_mov_b32_e32 v6, v2
	v_mov_b32_e32 v7, v2
	v_mov_b32_e32 v8, v2
	v_mov_b32_e32 v9, v2
	v_mov_b32_e32 v14, v2
	v_mov_b32_e32 v15, v2
	v_mov_b32_e32 v16, v2
	v_mov_b32_e32 v17, v2
	v_mov_b32_e32 v22, v2
	v_mov_b32_e32 v23, v2
	v_mov_b32_e32 v24, v2
	v_mov_b32_e32 v25, v2
	v_mov_b32_e32 v30, v2
	v_mov_b32_e32 v31, v2
	v_mov_b32_e32 v32, v2
	v_mov_b32_e32 v33, v2
	v_mov_b32_e32 v38, v2
	v_mov_b32_e32 v39, v2
	v_mov_b32_e32 v40, v2
	v_mov_b32_e32 v41, v2
	v_mov_b32_e32 v46, v2
	v_mov_b32_e32 v47, v2
	v_mov_b32_e32 v48, v2
	v_mov_b32_e32 v49, v2
	v_mov_b32_e32 v54, v2
	v_mov_b32_e32 v55, v2
	v_mov_b32_e32 v56, v2
	v_mov_b32_e32 v57, v2
	v_mov_b32_e32 v10, v2
	v_mov_b32_e32 v11, v2
	v_mov_b32_e32 v12, v2
	v_mov_b32_e32 v13, v2
	v_mov_b32_e32 v18, v2
	v_mov_b32_e32 v19, v2
	v_mov_b32_e32 v20, v2
	v_mov_b32_e32 v21, v2
	v_mov_b32_e32 v26, v2
	v_mov_b32_e32 v27, v2
	v_mov_b32_e32 v28, v2
	v_mov_b32_e32 v29, v2
	v_mov_b32_e32 v34, v2
	v_mov_b32_e32 v35, v2
	v_mov_b32_e32 v36, v2
	v_mov_b32_e32 v37, v2
	v_mov_b32_e32 v42, v2
	v_mov_b32_e32 v43, v2
	v_mov_b32_e32 v44, v2
	v_mov_b32_e32 v45, v2
	v_mov_b32_e32 v50, v2
	v_mov_b32_e32 v51, v2
	v_mov_b32_e32 v52, v2
	v_mov_b32_e32 v53, v2
	v_mov_b32_e32 v58, v2
	v_mov_b32_e32 v59, v2
	v_mov_b32_e32 v60, v2
	v_mov_b32_e32 v61, v2
	v_mov_b32_e32 v62, v2
	v_mov_b32_e32 v63, v2
	v_mov_b32_e32 v64, v2
	v_mov_b32_e32 v65, v2
	v_mov_b32_e32 v66, v2
	v_mov_b32_e32 v67, v2
	v_mov_b32_e32 v68, v2
	v_mov_b32_e32 v69, v2
	v_mov_b32_e32 v70, v2
	v_mov_b32_e32 v71, v2
	v_mov_b32_e32 v72, v2
	v_mov_b32_e32 v73, v2
	v_mov_b32_e32 v78, v2
	v_mov_b32_e32 v79, v2
	v_mov_b32_e32 v80, v2
	v_mov_b32_e32 v81, v2
	v_mov_b32_e32 v86, v2
	v_mov_b32_e32 v87, v2
	v_mov_b32_e32 v88, v2
	v_mov_b32_e32 v89, v2
	v_mov_b32_e32 v94, v2
	v_mov_b32_e32 v95, v2
	v_mov_b32_e32 v96, v2
	v_mov_b32_e32 v97, v2
	v_mov_b32_e32 v102, v2
	v_mov_b32_e32 v103, v2
	v_mov_b32_e32 v104, v2
	v_mov_b32_e32 v105, v2
	v_mov_b32_e32 v110, v2
	v_mov_b32_e32 v111, v2
	v_mov_b32_e32 v112, v2
	v_mov_b32_e32 v113, v2
	v_mov_b32_e32 v118, v2
	v_mov_b32_e32 v119, v2
	v_mov_b32_e32 v120, v2
	v_mov_b32_e32 v121, v2
	v_mov_b32_e32 v74, v2
	v_mov_b32_e32 v75, v2
	v_mov_b32_e32 v76, v2
	v_mov_b32_e32 v77, v2
	v_mov_b32_e32 v82, v2
	v_mov_b32_e32 v83, v2
	v_mov_b32_e32 v84, v2
	v_mov_b32_e32 v85, v2
	v_mov_b32_e32 v90, v2
	v_mov_b32_e32 v91, v2
	v_mov_b32_e32 v92, v2
	v_mov_b32_e32 v93, v2
	v_mov_b32_e32 v98, v2
	v_mov_b32_e32 v99, v2
	v_mov_b32_e32 v100, v2
	v_mov_b32_e32 v101, v2
	v_mov_b32_e32 v106, v2
	v_mov_b32_e32 v107, v2
	v_mov_b32_e32 v108, v2
	v_mov_b32_e32 v109, v2
	v_mov_b32_e32 v114, v2
	v_mov_b32_e32 v115, v2
	v_mov_b32_e32 v116, v2
	v_mov_b32_e32 v117, v2
	v_mov_b32_e32 v122, v2
	v_mov_b32_e32 v123, v2
	v_mov_b32_e32 v124, v2
	v_mov_b32_e32 v125, v2
	v_mov_b32_e32 v126, v2
	v_mov_b32_e32 v127, v2
	v_mov_b32_e32 v128, v2
	v_mov_b32_e32 v129, v2
	.p2align	6

; template <class Epi, class Sched, bool ALIGN_EPI = false, bool SP2 = false>
; __device__ __forceinline__ void gemm_phase(PG8_LAS unsigned char* lds, const Gemm g, const Sched& S, const Epi& E) {
;     ...
;     f32x4 acc[2][2][4][2];
; #pragma unroll
;     for (int a = 0; a < 2; ++a)
; #pragma unroll
;         for (int b = 0; b < 2; ++b)
; #pragma unroll
;             for (int m = 0; m < 4; ++m)
; #pragma unroll
;                 for (int n = 0; n < 2; ++n) acc[a][b][m][n] = (f32x4){0.f, 0.f, 0.f, 0.f};
;     ...
;         const char* nA = has_next ? (const char*)g.A + (size_t)nxt.pm * tstep : cA; const char* nB = has_next ? (const char*)g.Bt + (size_t)nxt.pn * tstep : cB;
;         for (int t = 0; t < nt; t += 2) {
;             const bool last = (t == nt - 2);
;             const char* a1 = cA + (size_t)(t + 1) * kstep;
;             const char* a2 = last ? nA : cA + (size_t)(t + 2) * kstep; const char* b2 = last ? nB : cB + (size_t)(t + 2) * kstep;
;             const char* a3 = a2 + kstep; const char* b3 = b2 + kstep;
.LBB0_816:
	s_add_u32 s40, s40, 0x80
	s_addc_u32 s41, s41, 0
	s_add_u32 s73, s6, 0x100
	v_mov_b32_e32 v2, 0
	s_addc_u32 s74, s7, 0
	s_mov_b32 s6, 0
	v_mov_b32_e32 v3, v2
	v_mov_b32_e32 v4, v2
	v_mov_b32_e32 v5, v2
	v_mov_b32_e32 v6, v2
	v_mov_b32_e32 v7, v2
	v_mov_b32_e32 v8, v2
	v_mov_b32_e32 v9, v2
	v_mov_b32_e32 v10, v2
	v_mov_b32_e32 v11, v2
	v_mov_b32_e32 v12, v2
	v_mov_b32_e32 v13, v2
	v_mov_b32_e32 v14, v2
	v_mov_b32_e32 v15, v2
	v_mov_b32_e32 v16, v2
	v_mov_b32_e32 v17, v2
	v_mov_b32_e32 v18, v2
	v_mov_b32_e32 v19, v2
	v_mov_b32_e32 v20, v2
	v_mov_b32_e32 v21, v2
	v_mov_b32_e32 v22, v2
	v_mov_b32_e32 v23, v2
	v_mov_b32_e32 v24, v2
	v_mov_b32_e32 v25, v2
	v_mov_b32_e32 v26, v2
	v_mov_b32_e32 v27, v2
	v_mov_b32_e32 v28, v2
	v_mov_b32_e32 v29, v2
	v_mov_b32_e32 v30, v2
	v_mov_b32_e32 v31, v2
	v_mov_b32_e32 v32, v2
	v_mov_b32_e32 v33, v2
	v_mov_b32_e32 v66, v2
	v_mov_b32_e32 v67, v2
	v_mov_b32_e32 v68, v2
	v_mov_b32_e32 v69, v2
	v_mov_b32_e32 v70, v2
	v_mov_b32_e32 v71, v2
	v_mov_b32_e32 v72, v2
	v_mov_b32_e32 v73, v2
	v_mov_b32_e32 v74, v2
	v_mov_b32_e32 v75, v2
	v_mov_b32_e32 v76, v2
	v_mov_b32_e32 v77, v2
	v_mov_b32_e32 v78, v2
	v_mov_b32_e32 v79, v2
	v_mov_b32_e32 v80, v2
	v_mov_b32_e32 v81, v2
	v_mov_b32_e32 v82, v2
	v_mov_b32_e32 v83, v2
	v_mov_b32_e32 v84, v2
	v_mov_b32_e32 v85, v2
	v_mov_b32_e32 v86, v2
	v_mov_b32_e32 v87, v2
	v_mov_b32_e32 v88, v2
	v_mov_b32_e32 v89, v2
	v_mov_b32_e32 v90, v2
	v_mov_b32_e32 v91, v2
	v_mov_b32_e32 v92, v2
	v_mov_b32_e32 v93, v2
	v_mov_b32_e32 v94, v2
	v_mov_b32_e32 v95, v2
	v_mov_b32_e32 v96, v2
	v_mov_b32_e32 v97, v2
	v_mov_b32_e32 v34, v2
	v_mov_b32_e32 v35, v2
	v_mov_b32_e32 v36, v2
	v_mov_b32_e32 v37, v2
	v_mov_b32_e32 v38, v2
	v_mov_b32_e32 v39, v2
	v_mov_b32_e32 v40, v2
	v_mov_b32_e32 v41, v2
	v_mov_b32_e32 v42, v2
	v_mov_b32_e32 v43, v2
	v_mov_b32_e32 v44, v2
	v_mov_b32_e32 v45, v2
	v_mov_b32_e32 v46, v2
	v_mov_b32_e32 v47, v2
	v_mov_b32_e32 v48, v2
	v_mov_b32_e32 v49, v2
	v_mov_b32_e32 v50, v2
	v_mov_b32_e32 v51, v2
	v_mov_b32_e32 v52, v2
	v_mov_b32_e32 v53, v2
	v_mov_b32_e32 v54, v2
	v_mov_b32_e32 v55, v2
	v_mov_b32_e32 v56, v2
	v_mov_b32_e32 v57, v2
	v_mov_b32_e32 v58, v2
	v_mov_b32_e32 v59, v2
	v_mov_b32_e32 v60, v2
	v_mov_b32_e32 v61, v2
	v_mov_b32_e32 v62, v2
	v_mov_b32_e32 v63, v2
	v_mov_b32_e32 v64, v2
	v_mov_b32_e32 v65, v2
	v_mov_b32_e32 v98, v2
	v_mov_b32_e32 v99, v2
	v_mov_b32_e32 v100, v2
	v_mov_b32_e32 v101, v2
	v_mov_b32_e32 v102, v2
	v_mov_b32_e32 v103, v2
	v_mov_b32_e32 v104, v2
	v_mov_b32_e32 v105, v2
	v_mov_b32_e32 v106, v2
	v_mov_b32_e32 v107, v2
	v_mov_b32_e32 v108, v2
	v_mov_b32_e32 v109, v2
	v_mov_b32_e32 v110, v2
	v_mov_b32_e32 v111, v2
	v_mov_b32_e32 v112, v2
	v_mov_b32_e32 v113, v2
	v_mov_b32_e32 v114, v2
	v_mov_b32_e32 v115, v2
	v_mov_b32_e32 v116, v2
	v_mov_b32_e32 v117, v2
	v_mov_b32_e32 v118, v2
	v_mov_b32_e32 v119, v2
	v_mov_b32_e32 v120, v2
	v_mov_b32_e32 v121, v2
	v_mov_b32_e32 v122, v2
	v_mov_b32_e32 v123, v2
	v_mov_b32_e32 v124, v2
	v_mov_b32_e32 v125, v2
	v_mov_b32_e32 v126, v2
	v_mov_b32_e32 v127, v2
	v_mov_b32_e32 v128, v2
	v_mov_b32_e32 v129, v2
	.p2align	6

;     __device__ __forceinline__ bool next(int i, Unit& u) const { Unit t; if (!base.next(i / 3, t)) return false; const int br = i % 3; u.pm = t.pm + 128 * br; u.pn = t.pn + 4 * br; return true; }
; template <class Epi, class Sched, bool ALIGN_EPI = false, bool SP2 = false>
; __device__ __forceinline__ void gemm_phase(PG8_LAS unsigned char* lds, const Gemm g, const Sched& S, const Epi& E) {
;     ...
;     f32x4 acc[2][2][4][2];
; #pragma unroll
;     for (int a = 0; a < 2; ++a)
; #pragma unroll
;         for (int b = 0; b < 2; ++b)
; #pragma unroll
;             for (int m = 0; m < 4; ++m)
; #pragma unroll
;                 for (int n = 0; n < 2; ++n) acc[a][b][m][n] = (f32x4){0.f, 0.f, 0.f, 0.f};
;     ...
;         const bool has_next = S.next(ui + 1, nxt);
;         const char* nA = has_next ? (const char*)g.A + (size_t)nxt.pm * tstep : cA; const char* nB = has_next ? (const char*)g.Bt + (size_t)nxt.pn * tstep : cB;
;         for (int t = 0; t < nt; t += 2) {
;             const bool last = (t == nt - 2);
;             const char* a1 = cA + (size_t)(t + 1) * kstep;
;             const char* a2 = last ? nA : cA + (size_t)(t + 2) * kstep; const char* b2 = last ? nB : cB + (size_t)(t + 2) * kstep;
;             const char* a3 = a2 + kstep; const char* b3 = b2 + kstep;
.LBB0_872:
	s_ashr_i32 s41, s40, 31
	s_lshl_b64 s[42:43], s[40:41], 19
	s_add_u32 s42, s72, s42
	s_addc_u32 s43, s73, s43
	s_and_b64 s[44:45], s[38:39], exec
	s_cselect_b32 s41, s43, s49
	s_cselect_b32 s65, s42, s48
	s_ashr_i32 s31, s30, 31
	s_lshl_b64 s[44:45], s[30:31], 19
	s_add_u32 s44, s5, s44
	s_addc_u32 s45, s10, s45
	s_and_b64 s[50:51], s[38:39], exec
	s_cselect_b32 s31, s45, s7
	s_cselect_b32 s66, s44, s6
	s_add_u32 s48, s48, 0x40080
	s_addc_u32 s49, s49, 0
	s_add_u32 s67, s6, 0x100
	v_mov_b32_e32 v2, 0
	s_addc_u32 s68, s7, 0
	s_mov_b32 s69, -2
	v_mov_b32_e32 v3, v2
	v_mov_b32_e32 v4, v2
	v_mov_b32_e32 v5, v2
	v_mov_b32_e32 v6, v2
	v_mov_b32_e32 v7, v2
	v_mov_b32_e32 v8, v2
	v_mov_b32_e32 v9, v2
	v_mov_b32_e32 v18, v2
	v_mov_b32_e32 v19, v2
	v_mov_b32_e32 v20, v2
	v_mov_b32_e32 v21, v2
	v_mov_b32_e32 v22, v2
	v_mov_b32_e32 v23, v2
	v_mov_b32_e32 v24, v2
	v_mov_b32_e32 v25, v2
	v_mov_b32_e32 v34, v2
	v_mov_b32_e32 v35, v2
	v_mov_b32_e32 v36, v2
	v_mov_b32_e32 v37, v2
	v_mov_b32_e32 v38, v2
	v_mov_b32_e32 v39, v2
	v_mov_b32_e32 v40, v2
	v_mov_b32_e32 v41, v2
	v_mov_b32_e32 v50, v2
	v_mov_b32_e32 v51, v2
	v_mov_b32_e32 v52, v2
	v_mov_b32_e32 v53, v2
	v_mov_b32_e32 v54, v2
	v_mov_b32_e32 v55, v2
	v_mov_b32_e32 v56, v2
	v_mov_b32_e32 v57, v2
	v_mov_b32_e32 v10, v2
	v_mov_b32_e32 v11, v2
	v_mov_b32_e32 v12, v2
	v_mov_b32_e32 v13, v2
	v_mov_b32_e32 v14, v2
	v_mov_b32_e32 v15, v2
	v_mov_b32_e32 v16, v2
	v_mov_b32_e32 v17, v2
	v_mov_b32_e32 v26, v2
	v_mov_b32_e32 v27, v2
	v_mov_b32_e32 v28, v2
	v_mov_b32_e32 v29, v2
	v_mov_b32_e32 v30, v2
	v_mov_b32_e32 v31, v2
	v_mov_b32_e32 v32, v2
	v_mov_b32_e32 v33, v2
	v_mov_b32_e32 v42, v2
	v_mov_b32_e32 v43, v2
	v_mov_b32_e32 v44, v2
	v_mov_b32_e32 v45, v2
	v_mov_b32_e32 v46, v2
	v_mov_b32_e32 v47, v2
	v_mov_b32_e32 v48, v2
	v_mov_b32_e32 v49, v2
	v_mov_b32_e32 v58, v2
	v_mov_b32_e32 v59, v2
	v_mov_b32_e32 v60, v2
	v_mov_b32_e32 v61, v2
	v_mov_b32_e32 v62, v2
	v_mov_b32_e32 v63, v2
	v_mov_b32_e32 v64, v2
	v_mov_b32_e32 v65, v2
	v_mov_b32_e32 v66, v2
	v_mov_b32_e32 v67, v2
	v_mov_b32_e32 v68, v2
	v_mov_b32_e32 v69, v2
	v_mov_b32_e32 v70, v2
	v_mov_b32_e32 v71, v2
	v_mov_b32_e32 v72, v2
	v_mov_b32_e32 v73, v2
	v_mov_b32_e32 v82, v2
	v_mov_b32_e32 v83, v2
	v_mov_b32_e32 v84, v2
	v_mov_b32_e32 v85, v2
	v_mov_b32_e32 v86, v2
	v_mov_b32_e32 v87, v2
	v_mov_b32_e32 v88, v2
	v_mov_b32_e32 v89, v2
	v_mov_b32_e32 v98, v2
	v_mov_b32_e32 v99, v2
	v_mov_b32_e32 v100, v2
	v_mov_b32_e32 v101, v2
	v_mov_b32_e32 v102, v2
	v_mov_b32_e32 v103, v2
	v_mov_b32_e32 v104, v2
	v_mov_b32_e32 v105, v2
	v_mov_b32_e32 v114, v2
	v_mov_b32_e32 v115, v2
	v_mov_b32_e32 v116, v2
	v_mov_b32_e32 v117, v2
	v_mov_b32_e32 v118, v2
	v_mov_b32_e32 v119, v2
	v_mov_b32_e32 v120, v2
	v_mov_b32_e32 v121, v2
	v_mov_b32_e32 v74, v2
	v_mov_b32_e32 v75, v2
	v_mov_b32_e32 v76, v2
	v_mov_b32_e32 v77, v2
	v_mov_b32_e32 v78, v2
	v_mov_b32_e32 v79, v2
	v_mov_b32_e32 v80, v2
	v_mov_b32_e32 v81, v2
	v_mov_b32_e32 v90, v2
	v_mov_b32_e32 v91, v2
	v_mov_b32_e32 v92, v2
	v_mov_b32_e32 v93, v2
	v_mov_b32_e32 v94, v2
	v_mov_b32_e32 v95, v2
	v_mov_b32_e32 v96, v2
	v_mov_b32_e32 v97, v2
	v_mov_b32_e32 v106, v2
	v_mov_b32_e32 v107, v2
	v_mov_b32_e32 v108, v2
	v_mov_b32_e32 v109, v2
	v_mov_b32_e32 v110, v2
	v_mov_b32_e32 v111, v2
	v_mov_b32_e32 v112, v2
	v_mov_b32_e32 v113, v2
	v_mov_b32_e32 v122, v2
	v_mov_b32_e32 v123, v2
	v_mov_b32_e32 v124, v2
	v_mov_b32_e32 v125, v2
	v_mov_b32_e32 v126, v2
	v_mov_b32_e32 v127, v2
	v_mov_b32_e32 v128, v2
	v_mov_b32_e32 v129, v2
	.p2align	6
